# xl_minigemm epilogue: both halves' row sums loaded in one round trip, closing barrier does not wait for XL stores
# baseline (speedup 1.0000x reference)
.LBB0_647:
	v_or_b32_e32 v66, s1, v1
	v_ashrrev_i32_e32 v67, 31, v66
	v_lshlrev_b64 v[68:69], 6, v[66:67]
	v_lshl_add_u64 v[80:81], s[24:25], 0, v[68:69]
	v_or_b32_e32 v116, 32, v66
	v_ashrrev_i32_e32 v117, 31, v116
	v_lshlrev_b64 v[118:119], 6, v[116:117]
	v_lshl_add_u64 v[114:115], s[24:25], 0, v[118:119]
	global_load_dwordx4 v[68:71], v[80:81], off offset:48
	global_load_dwordx4 v[72:75], v[80:81], off offset:32
	global_load_dwordx4 v[76:79], v[80:81], off offset:16
	s_nop 0
	global_load_dwordx4 v[80:83], v[80:81], off
	global_load_dwordx4 v[98:101], v[114:115], off offset:48
	global_load_dwordx4 v[102:105], v[114:115], off offset:32
	global_load_dwordx4 v[106:109], v[114:115], off offset:16
	global_load_dwordx4 v[110:113], v[114:115], off
	s_add_i32 s0, s0, s87
	s_cmpk_gt_i32 s0, 0xff
	s_waitcnt vmcnt(6)
	v_add_f32_e32 v72, v72, v73
	v_add_f32_e32 v74, v74, v75
	s_waitcnt vmcnt(4)
	v_mov_b32_e32 v84, v81
	v_mov_b32_e32 v85, v82
	v_mov_b32_e32 v81, v83
	v_mov_b32_e32 v82, v77
	v_mov_b32_e32 v83, v78
	v_mov_b32_e32 v77, v79
	v_pk_add_f32 v[80:81], v[84:85], v[80:81]
	v_pk_add_f32 v[76:77], v[82:83], v[76:77]
	v_pk_add_f32 v[80:81], v[80:81], v[80:81] op_sel:[0,1] op_sel_hi:[1,0]
	v_pk_add_f32 v[76:77], v[76:77], v[76:77] op_sel:[0,1] op_sel_hi:[1,0]
	v_mov_b32_e32 v81, v68
	v_mov_b32_e32 v77, v69
	v_mov_b32_e32 v73, v70
	v_mov_b32_e32 v75, v71
	v_pk_add_f32 v[68:69], v[80:81], v[76:77]
	v_pk_add_f32 v[70:71], v[72:73], v[74:75]
	s_nop 0
	v_pk_add_f32 v[68:69], v[68:69], v[70:71]
	v_lshlrev_b64 v[70:71], 9, v[66:67]
	v_add_f32_e32 v68, v68, v69
	v_fmamk_f32 v68, v68, 0x3a800000, v220
	v_rsq_f32_e32 v68, v68
	v_lshl_add_u64 v[70:71], v[164:165], 0, v[70:71]
	s_waitcnt vmcnt(0)
	v_add_f32_e32 v102, v102, v103
	v_add_f32_e32 v104, v104, v105
	v_mov_b32_e32 v120, v111
	v_mov_b32_e32 v121, v112
	v_mov_b32_e32 v111, v113
	v_mov_b32_e32 v112, v107
	v_mov_b32_e32 v113, v108
	v_mov_b32_e32 v107, v109
	v_pk_add_f32 v[110:111], v[120:121], v[110:111]
	v_pk_add_f32 v[106:107], v[112:113], v[106:107]
	v_pk_add_f32 v[110:111], v[110:111], v[110:111] op_sel:[0,1] op_sel_hi:[1,0]
	v_pk_add_f32 v[106:107], v[106:107], v[106:107] op_sel:[0,1] op_sel_hi:[1,0]
	v_mov_b32_e32 v111, v98
	v_mov_b32_e32 v107, v99
	v_mov_b32_e32 v103, v100
	v_mov_b32_e32 v105, v101
	v_pk_add_f32 v[98:99], v[110:111], v[106:107]
	v_pk_add_f32 v[100:101], v[102:103], v[104:105]
	s_nop 0
	v_pk_add_f32 v[98:99], v[98:99], v[100:101]
	v_lshlrev_b64 v[100:101], 9, v[116:117]
	v_add_f32_e32 v98, v98, v99
	v_fmamk_f32 v98, v98, 0x3a800000, v220
	v_rsq_f32_e32 v98, v98
	v_lshl_add_u64 v[100:101], v[164:165], 0, v[100:101]
	v_pk_mul_f32 v[18:19], v[18:19], v[68:69] op_sel_hi:[1,0]
	v_pk_mul_f32 v[20:21], v[20:21], v[68:69] op_sel_hi:[1,0]
	v_cvt_pk_bf16_f32 v18, v18, v19
	v_cvt_pk_bf16_f32 v19, v20, v21
	global_store_dwordx2 v[70:71], v[18:19], off
	v_pk_mul_f32 v[18:19], v[22:23], v[68:69] op_sel_hi:[1,0]
	v_pk_mul_f32 v[20:21], v[24:25], v[68:69] op_sel_hi:[1,0]
	v_cvt_pk_bf16_f32 v18, v18, v19
	v_cvt_pk_bf16_f32 v19, v20, v21
	global_store_dwordx2 v[70:71], v[18:19], off offset:16
	v_pk_mul_f32 v[18:19], v[26:27], v[68:69] op_sel_hi:[1,0]
	v_pk_mul_f32 v[20:21], v[28:29], v[68:69] op_sel_hi:[1,0]
	v_cvt_pk_bf16_f32 v18, v18, v19
	v_cvt_pk_bf16_f32 v19, v20, v21
	global_store_dwordx2 v[70:71], v[18:19], off offset:32
	v_pk_mul_f32 v[18:19], v[30:31], v[68:69] op_sel_hi:[1,0]
	v_pk_mul_f32 v[20:21], v[32:33], v[68:69] op_sel_hi:[1,0]
	v_cvt_pk_bf16_f32 v18, v18, v19
	v_cvt_pk_bf16_f32 v19, v20, v21
	global_store_dwordx2 v[70:71], v[18:19], off offset:48
	v_pk_mul_f32 v[2:3], v[2:3], v[98:99] op_sel_hi:[1,0]
	v_pk_mul_f32 v[4:5], v[4:5], v[98:99] op_sel_hi:[1,0]
	v_cvt_pk_bf16_f32 v2, v2, v3
	v_cvt_pk_bf16_f32 v3, v4, v5
	global_store_dwordx2 v[100:101], v[2:3], off
	v_pk_mul_f32 v[2:3], v[6:7], v[98:99] op_sel_hi:[1,0]
	v_pk_mul_f32 v[4:5], v[8:9], v[98:99] op_sel_hi:[1,0]
	v_cvt_pk_bf16_f32 v2, v2, v3
	v_cvt_pk_bf16_f32 v3, v4, v5
	global_store_dwordx2 v[100:101], v[2:3], off offset:16
	v_pk_mul_f32 v[2:3], v[10:11], v[98:99] op_sel_hi:[1,0]
	v_pk_mul_f32 v[4:5], v[12:13], v[98:99] op_sel_hi:[1,0]
	v_cvt_pk_bf16_f32 v2, v2, v3
	v_cvt_pk_bf16_f32 v3, v4, v5
	global_store_dwordx2 v[100:101], v[2:3], off offset:32
	v_pk_mul_f32 v[2:3], v[14:15], v[98:99] op_sel_hi:[1,0]
	v_pk_mul_f32 v[4:5], v[16:17], v[98:99] op_sel_hi:[1,0]
	v_cvt_pk_bf16_f32 v2, v2, v3
	v_cvt_pk_bf16_f32 v3, v4, v5
	global_store_dwordx2 v[100:101], v[2:3], off offset:48
	s_waitcnt lgkmcnt(0)
	s_barrier
	s_cbranch_scc1 .LBB0_653
